# v45 plus: five needless s_waitcnt vmcnt(0) removed from the P1 (input projection) epilogue - they had no pending register load on their path and only stalled on the stores just issued
# baseline (speedup 1.0000x reference)
;     __device__ __forceinline__ void operator()(const f32x4 (&acc)[2][2][4][2], const Unit& u, int wr, int wc, int fr, int fq) const {
;     ...
;                 f32x4 c0 = {1.f, 1.f, 1.f, 1.f}, c1 = c0, s0 = {0.f, 0.f, 0.f, 0.f}, s1 = s0;
;                 if (ropew) { c0 = rc[m][0]; c1 = rc[m][1]; s0 = rc[m][2]; s1 = rc[m][3]; if (fq == 0) { s0 = -s0; s1 = -s1; } if (fq >= 2) { c0 = (f32x4){1.f, 1.f, 1.f, 1.f}; c1 = c0; s0 = (f32x4){0.f, 0.f, 0.f, 0.f}; s1 = s0; } }
.LBB0_305:
	v_xor_b32_e32 v177, 0x80000000, v127
	v_xor_b32_e32 v178, 0x80000000, v126
	v_xor_b32_e32 v179, 0x80000000, v125
	v_xor_b32_e32 v180, 0x80000000, v124
	v_xor_b32_e32 v181, 0x80000000, v123
	v_xor_b32_e32 v186, 0x80000000, v122
	v_xor_b32_e32 v183, 0x80000000, v121
	v_xor_b32_e32 v182, 0x80000000, v120
	v_cndmask_b32_e64 v188, v124, v180, s[4:5]
	v_cndmask_b32_e64 v189, v125, v179, s[4:5]
	v_cndmask_b32_e64 v190, v126, v178, s[4:5]
	v_cndmask_b32_e64 v191, v127, v177, s[4:5]
	v_cndmask_b32_e64 v182, v120, v182, s[4:5]
	v_cndmask_b32_e64 v183, v121, v183, s[4:5]
	v_cndmask_b32_e64 v180, v122, v186, s[4:5]
	v_cndmask_b32_e64 v181, v123, v181, s[4:5]
	v_mov_b32_e32 v179, v99
	v_mov_b32_e32 v178, v98
	v_mov_b32_e32 v187, v97
	v_mov_b32_e32 v186, v96
	v_mov_b32_e32 v211, v103
	v_mov_b32_e32 v210, v102
	v_mov_b32_e32 v215, v101
	v_mov_b32_e32 v214, v100
	s_and_saveexec_b64 s[0:1], s[6:7]
	s_cbranch_execz .LBB0_307
	v_mov_b32_e32 v179, 1.0
	v_mov_b32_e32 v181, 0
	v_mov_b32_e32 v180, 0
	v_mov_b32_e32 v183, 0
	v_mov_b32_e32 v182, v181
	v_mov_b32_e32 v191, 0
	v_mov_b32_e32 v190, 0
	v_mov_b32_e32 v189, 0
	v_mov_b32_e32 v188, v181
	v_mov_b32_e32 v178, 1.0
	v_mov_b32_e32 v187, 1.0
	v_mov_b32_e32 v186, v179
	v_mov_b32_e32 v211, 1.0
	v_mov_b32_e32 v210, 1.0
	v_mov_b32_e32 v215, 1.0
	v_mov_b32_e32 v214, v179

;     __device__ __forceinline__ void operator()(const f32x4 (&acc)[2][2][4][2], const Unit& u, int wr, int wc, int fr, int fq) const {
;     ...
;                 f32x4 c0 = {1.f, 1.f, 1.f, 1.f}, c1 = c0, s0 = {0.f, 0.f, 0.f, 0.f}, s1 = s0;
;                 if (ropew) { c0 = rc[m][0]; c1 = rc[m][1]; s0 = rc[m][2]; s1 = rc[m][3]; if (fq == 0) { s0 = -s0; s1 = -s1; } if (fq >= 2) { c0 = (f32x4){1.f, 1.f, 1.f, 1.f}; c1 = c0; s0 = (f32x4){0.f, 0.f, 0.f, 0.f}; s1 = s0; } }
.LBB0_325:
	v_xor_b32_e32 v161, 0x80000000, v95
	v_xor_b32_e32 v162, 0x80000000, v94
	v_xor_b32_e32 v163, 0x80000000, v93
	v_xor_b32_e32 v164, 0x80000000, v92
	v_xor_b32_e32 v165, 0x80000000, v91
	v_xor_b32_e32 v168, 0x80000000, v90
	v_xor_b32_e32 v167, 0x80000000, v89
	v_xor_b32_e32 v166, 0x80000000, v88
	v_cndmask_b32_e64 v170, v92, v164, s[4:5]
	v_cndmask_b32_e64 v171, v93, v163, s[4:5]
	v_cndmask_b32_e64 v172, v94, v162, s[4:5]
	v_cndmask_b32_e64 v173, v95, v161, s[4:5]
	v_cndmask_b32_e64 v166, v88, v166, s[4:5]
	v_cndmask_b32_e64 v167, v89, v167, s[4:5]
	v_cndmask_b32_e64 v164, v90, v168, s[4:5]
	v_cndmask_b32_e64 v165, v91, v165, s[4:5]
	v_mov_b32_e32 v163, v79
	v_mov_b32_e32 v162, v78
	v_mov_b32_e32 v169, v77
	v_mov_b32_e32 v168, v76
	v_mov_b32_e32 v175, v87
	v_mov_b32_e32 v174, v86
	v_mov_b32_e32 v177, v85
	v_mov_b32_e32 v176, v84
	s_and_saveexec_b64 s[0:1], s[6:7]
	s_cbranch_execz .LBB0_327
	v_mov_b32_e32 v163, 1.0
	v_mov_b32_e32 v165, 0
	v_mov_b32_e32 v164, 0
	v_mov_b32_e32 v167, 0
	v_mov_b32_e32 v166, v165
	v_mov_b32_e32 v173, 0
	v_mov_b32_e32 v172, 0
	v_mov_b32_e32 v171, 0
	v_mov_b32_e32 v170, v165
	v_mov_b32_e32 v162, 1.0
	v_mov_b32_e32 v169, 1.0
	v_mov_b32_e32 v168, v163
	v_mov_b32_e32 v175, 1.0
	v_mov_b32_e32 v174, 1.0
	v_mov_b32_e32 v177, 1.0
	v_mov_b32_e32 v176, v163

;     __device__ __forceinline__ void operator()(const f32x4 (&acc)[2][2][4][2], const Unit& u, int wr, int wc, int fr, int fq) const {
;     ...
;                 f32x4 c0 = {1.f, 1.f, 1.f, 1.f}, c1 = c0, s0 = {0.f, 0.f, 0.f, 0.f}, s1 = s0;
;                 if (ropew) { c0 = rc[m][0]; c1 = rc[m][1]; s0 = rc[m][2]; s1 = rc[m][3]; if (fq == 0) { s0 = -s0; s1 = -s1; } if (fq >= 2) { c0 = (f32x4){1.f, 1.f, 1.f, 1.f}; c1 = c0; s0 = (f32x4){0.f, 0.f, 0.f, 0.f}; s1 = s0; } }
.LBB0_345:
	v_xor_b32_e32 v137, 0x80000000, v63
	v_xor_b32_e32 v138, 0x80000000, v62
	v_xor_b32_e32 v139, 0x80000000, v61
	v_xor_b32_e32 v140, 0x80000000, v60
	v_xor_b32_e32 v141, 0x80000000, v59
	v_xor_b32_e32 v148, 0x80000000, v58
	v_xor_b32_e32 v143, 0x80000000, v57
	v_xor_b32_e32 v142, 0x80000000, v56
	v_cndmask_b32_e64 v150, v60, v140, s[4:5]
	v_cndmask_b32_e64 v151, v61, v139, s[4:5]
	v_cndmask_b32_e64 v156, v62, v138, s[4:5]
	v_cndmask_b32_e64 v157, v63, v137, s[4:5]
	v_cndmask_b32_e64 v142, v56, v142, s[4:5]
	v_cndmask_b32_e64 v143, v57, v143, s[4:5]
	v_cndmask_b32_e64 v140, v58, v148, s[4:5]
	v_cndmask_b32_e64 v141, v59, v141, s[4:5]
	v_mov_b32_e32 v139, v51
	v_mov_b32_e32 v138, v50
	v_mov_b32_e32 v149, v49
	v_mov_b32_e32 v148, v48
	v_mov_b32_e32 v159, v55
	v_mov_b32_e32 v158, v54
	v_mov_b32_e32 v161, v53
	v_mov_b32_e32 v160, v52
	s_and_saveexec_b64 s[0:1], s[6:7]
	s_cbranch_execz .LBB0_347
	v_mov_b32_e32 v139, 1.0
	v_mov_b32_e32 v141, 0
	v_mov_b32_e32 v140, 0
	v_mov_b32_e32 v143, 0
	v_mov_b32_e32 v142, v141
	v_mov_b32_e32 v157, 0
	v_mov_b32_e32 v156, 0
	v_mov_b32_e32 v151, 0
	v_mov_b32_e32 v150, v141
	v_mov_b32_e32 v138, 1.0
	v_mov_b32_e32 v149, 1.0
	v_mov_b32_e32 v148, v139
	v_mov_b32_e32 v159, 1.0
	v_mov_b32_e32 v158, 1.0
	v_mov_b32_e32 v161, 1.0
	v_mov_b32_e32 v160, v139

; __device__ __forceinline__ unsigned cvt_pk_bf16(float lo, float hi) { unsigned r; asm volatile("v_cvt_pk_bf16_f32 %0, %1, %2" : "=v"(r) : "v"(lo), "v"(hi)); return r; }
;     __device__ __forceinline__ void operator()(const f32x4 (&acc)[2][2][4][2], const Unit& u, int wr, int wc, int fr, int fq) const {
;     ...
;             if (ropew) {
; #pragma unroll
;                 for (int m = 0; m < 4; ++m) { const f32x4* rp = (const f32x4*)(rope + (size_t)((row0 + ai * HALF + m * 16) & 4095) * 16); rc[m][0] = rp[0]; rc[m][1] = rp[1]; rc[m][2] = rp[2]; rc[m][3] = rp[3]; }
;     ...
;                     u32x4 w; w.x = cvt_pk_bf16(v0[0], v0[1]); w.y = cvt_pk_bf16(v0[2], v0[3]); w.z = cvt_pk_bf16(v1[0], v1[1]); w.w = cvt_pk_bf16(v1[2], v1[3]);
;                     *(u32x4*)(rowp + bj * HALF) = w;
.LBB0_362:
	s_and_b64 vcc, exec, s[12:13]
	v_cvt_pk_bf16_f32 v108, v108, v109
	v_cvt_pk_bf16_f32 v109, v110, v111
	v_cvt_pk_bf16_f32 v110, v104, v105
	v_cvt_pk_bf16_f32 v111, v106, v107
	global_store_dwordx4 v[112:113], v[108:111], off offset:256
	s_cbranch_vccnz .LBB0_364
	v_add_u32_e32 v48, 0x800, v251
	v_and_b32_e32 v48, 0xfcf0, v48
	v_lshlrev_b32_e32 v60, 2, v48
	global_load_dwordx4 v[128:131], v60, s[72:73] offset:16
	global_load_dwordx4 v[132:135], v60, s[72:73]
	global_load_dwordx4 v[144:147], v60, s[72:73] offset:48
	global_load_dwordx4 v[152:155], v60, s[72:73] offset:32
	global_load_dwordx4 v[96:99], v60, s[72:73] offset:1040
	global_load_dwordx4 v[100:103], v60, s[72:73] offset:1024
	global_load_dwordx4 v[120:123], v60, s[72:73] offset:1072
	global_load_dwordx4 v[124:127], v60, s[72:73] offset:1056
	global_load_dwordx4 v[76:79], v60, s[72:73] offset:2064
	global_load_dwordx4 v[84:87], v60, s[72:73] offset:2048
	global_load_dwordx4 v[88:91], v60, s[72:73] offset:2096
	global_load_dwordx4 v[92:95], v60, s[72:73] offset:2080
	global_load_dwordx4 v[48:51], v60, s[72:73] offset:3088
	global_load_dwordx4 v[52:55], v60, s[72:73] offset:3072
	global_load_dwordx4 v[56:59], v60, s[72:73] offset:3120
	s_nop 0
	global_load_dwordx4 v[60:63], v60, s[72:73] offset:3104

;     __device__ __forceinline__ void operator()(const f32x4 (&acc)[2][2][4][2], const Unit& u, int wr, int wc, int fr, int fq) const {
;     ...
;                 f32x4 c0 = {1.f, 1.f, 1.f, 1.f}, c1 = c0, s0 = {0.f, 0.f, 0.f, 0.f}, s1 = s0;
;                 if (ropew) { c0 = rc[m][0]; c1 = rc[m][1]; s0 = rc[m][2]; s1 = rc[m][3]; if (fq == 0) { s0 = -s0; s1 = -s1; } if (fq >= 2) { c0 = (f32x4){1.f, 1.f, 1.f, 1.f}; c1 = c0; s0 = (f32x4){0.f, 0.f, 0.f, 0.f}; s1 = s0; } }
.LBB0_372:
	v_mov_b32_e32 v110, 0
	v_mov_b32_e32 v132, 1.0
	v_mov_b32_e32 v133, v132
	v_mov_b32_e32 v134, v132
	v_mov_b32_e32 v135, v132
	v_mov_b32_e32 v128, v132
	v_mov_b32_e32 v129, v132
	v_mov_b32_e32 v130, v132
	v_mov_b32_e32 v131, v132
	v_mov_b32_e32 v111, v110
	v_mov_b32_e32 v112, v110
	v_mov_b32_e32 v113, v110
	v_mov_b32_e32 v108, v110
	v_mov_b32_e32 v109, v110
	v_mov_b32_e32 v106, v110
	v_mov_b32_e32 v107, v110
	s_and_b64 vcc, exec, s[12:13]
	s_cbranch_vccnz .LBB0_374
